# v56 + windowed attention (two-half step): next tile's LDS-DMA issue region moved behind the second QK MFMA
# speedup vs baseline: 1.0036x; 1.0029x over previous
.LBB0_1349:
	s_add_i32 s67, s0, 0xffffffa0
	s_cmp_gt_u32 s67, 0xffffff00
	s_cselect_b64 s[86:87], -1, 0
	s_cmpk_gt_i32 s0, 0xff60
	s_mov_b64 s[88:89], -1
	v_add_u32_e32 v214, v189, v199
	v_add_u32_e32 v213, v189, v203
	s_cbranch_scc0 .LBB0_1369
	ds_read_b128 v[34:37], v214
	ds_read_b128 v[106:109], v214 offset:2048
	ds_read_b128 v[102:105], v213
	ds_read_b128 v[98:101], v213 offset:2048
	ds_read_b128 v[94:97], v214 offset:4096
	ds_read_b128 v[90:93], v214 offset:6144
	ds_read_b128 v[86:89], v213 offset:4096
	ds_read_b128 v[82:85], v213 offset:6144
	s_waitcnt lgkmcnt(7)
	v_mfma_f32_32x32x16_bf16 v[50:65], v[34:37], v[130:133], v[66:81]
	s_waitcnt lgkmcnt(6)
	v_mfma_f32_32x32x16_bf16 v[34:49], v[106:109], v[130:133], v[66:81]
	s_add_i32 s67, s82, 1
	s_cmp_ge_i32 s67, s39
	s_cbranch_scc0 .LBB0_1354
	s_andn2_b64 vcc, exec, s[70:71]
	s_cbranch_vccnz .LBB0_1353
	s_xor_b32 s83, s96, 1
	s_mul_i32 s88, s83, 0x3000
	s_add_i32 s88, s88, s93
	s_mov_b32 s89, m0
	s_mov_b32 m0, s88
	s_nop 0
	global_load_lds_dwordx4 v1, s[74:75]
	s_mov_b32 m0, s89
	s_lshl_b32 s83, s83, 13
	s_add_i32 s83, s83, s94
	s_mov_b32 s88, m0
	s_mov_b32 m0, s83
	s_nop 0
	global_load_lds_dwordx4 v196, s[76:77]
	s_mov_b32 m0, s88

.LBB0_1356:
	s_waitcnt lgkmcnt(5)
	v_mfma_f32_32x32x16_bf16 v[50:65], v[102:105], v[138:141], v[50:65]
	s_waitcnt lgkmcnt(4)
	v_mfma_f32_32x32x16_bf16 v[34:49], v[98:101], v[138:141], v[34:49]
	s_waitcnt lgkmcnt(3)
	v_mfma_f32_32x32x16_bf16 v[50:65], v[94:97], v[134:137], v[50:65]
	v_lshl_add_u32 v94, s96, 13, v198
	ds_read_b64_tr_b16 v[174:175], v94 offset:24576
	ds_read_b64_tr_b16 v[176:177], v94 offset:25088
	ds_read_b64_tr_b16 v[170:171], v94 offset:25600
	ds_read_b64_tr_b16 v[172:173], v94 offset:26112
	ds_read_b64_tr_b16 v[166:167], v94 offset:26624
	ds_read_b64_tr_b16 v[168:169], v94 offset:27136
	ds_read_b64_tr_b16 v[162:163], v94 offset:27648
	ds_read_b64_tr_b16 v[164:165], v94 offset:28160
	ds_read_b64_tr_b16 v[158:159], v94 offset:28672
	ds_read_b64_tr_b16 v[160:161], v94 offset:29184
	ds_read_b64_tr_b16 v[154:155], v94 offset:29696
	ds_read_b64_tr_b16 v[156:157], v94 offset:30208
	ds_read_b64_tr_b16 v[150:151], v94 offset:30720
	ds_read_b64_tr_b16 v[152:153], v94 offset:31232
	ds_read_b64_tr_b16 v[146:147], v94 offset:31744
	ds_read_b64_tr_b16 v[148:149], v94 offset:32256
	s_waitcnt lgkmcnt(14)
	v_mfma_f32_32x32x16_bf16 v[34:49], v[90:93], v[134:137], v[34:49]
	v_mfma_f32_32x32x16_bf16 v[50:65], v[86:89], v[142:145], v[50:65]
	v_mfma_f32_32x32x16_bf16 v[34:49], v[82:85], v[142:145], v[34:49]
	v_cvt_f32_i32_e32 v82, v183
	s_mov_b64 s[88:89], -1
	s_andn2_b64 vcc, exec, s[84:85]
	v_sub_f32_e32 v83, 0, v82
	v_sub_f32_e32 v86, 1.0, v82
	v_and_b32_e32 v84, 0x7fffffff, v83
	v_and_b32_e32 v85, 0x7fffffff, v86
	s_cbranch_vccnz .LBB0_1358
	v_pk_add_f32 v[88:89], v[82:83], s[14:15] op_sel_hi:[0,1] neg_lo:[1,0] neg_hi:[1,0]
	v_pk_add_f32 v[90:91], v[82:83], s[36:37] op_sel_hi:[0,1] neg_lo:[1,0] neg_hi:[1,0]
	v_pk_add_f32 v[92:93], v[82:83], s[40:41] op_sel_hi:[0,1] neg_lo:[1,0] neg_hi:[1,0]
	v_pk_add_f32 v[94:95], v[82:83], s[54:55] op_sel_hi:[0,1] neg_lo:[1,0] neg_hi:[1,0]
	v_pk_add_f32 v[96:97], v[82:83], s[56:57] op_sel_hi:[0,1] neg_lo:[1,0] neg_hi:[1,0]
	v_pk_add_f32 v[98:99], v[82:83], s[42:43] op_sel_hi:[0,1] neg_lo:[1,0] neg_hi:[1,0]
	v_pk_add_f32 v[100:101], v[82:83], s[44:45] op_sel_hi:[0,1] neg_lo:[1,0] neg_hi:[1,0]
	v_and_b32_e32 v89, 0x7fffffff, v89
	v_and_b32_e32 v88, 0x7fffffff, v88
	v_and_b32_e32 v91, 0x7fffffff, v91
	v_and_b32_e32 v90, 0x7fffffff, v90
	v_and_b32_e32 v93, 0x7fffffff, v93
	v_and_b32_e32 v92, 0x7fffffff, v92
	v_and_b32_e32 v95, 0x7fffffff, v95
	v_and_b32_e32 v94, 0x7fffffff, v94
	v_and_b32_e32 v97, 0x7fffffff, v97
	v_and_b32_e32 v96, 0x7fffffff, v96
	v_and_b32_e32 v99, 0x7fffffff, v99
	v_and_b32_e32 v98, 0x7fffffff, v98
	v_and_b32_e32 v101, 0x7fffffff, v101
	v_and_b32_e32 v100, 0x7fffffff, v100
	v_mov_b32_e32 v193, v192
	v_pk_fma_f32 v[112:113], v[192:193], v[100:101], v[64:65]
	v_pk_fma_f32 v[110:111], v[192:193], v[98:99], v[62:63]
	v_pk_fma_f32 v[108:109], v[192:193], v[96:97], v[60:61]
	v_pk_fma_f32 v[106:107], v[192:193], v[94:95], v[58:59]
	v_pk_fma_f32 v[104:105], v[192:193], v[92:93], v[56:57]
	v_pk_fma_f32 v[102:103], v[192:193], v[90:91], v[54:55]
	v_pk_fma_f32 v[100:101], v[192:193], v[88:89], v[52:53]
	v_pk_fma_f32 v[98:99], v[194:195], v[84:85], v[50:51]
	s_mov_b64 s[88:89], 0
